# P2 epilogue stores sc0 sc1 nt
# speedup vs baseline: 1.0147x; 1.0147x over previous
; __device__ __forceinline__ unsigned cvt_pk_bf16(float lo, float hi) { unsigned r; asm volatile("v_cvt_pk_bf16_f32 %0, %1, %2" : "=v"(r) : "v"(lo), "v"(hi)); return r; }
;     __device__ __forceinline__ void operator()(const f32x4 (&acc)[2][2][4][2], const Unit& u, int wr, int wc, int fr, int fq) const {
;     ...
;             bf16_t* base; int ld, ct; float sc = 1.f;
;             if (pn < 4) { base = Q; ld = 1024; ct = pn; sc = qscale; } else if (pn < 8) { base = Kb; ld = 1024; ct = pn - 4; } else if (pn < 12) { base = V; ld = 1024; ct = pn - 8; }
;             else if (pn < 14) { base = U; ld = 512; ct = pn - 12; } else { base = G; ld = 2048; ct = pn - 14; }
;             const int row0 = u.pm * BM + wr * 64 + fr, col0 = ct * 256 + wc * 32 + 8 * fq;
; #pragma unroll
;             for (int ai = 0; ai < 2; ++ai)
; #pragma unroll
;                 for (int m = 0; m < 4; ++m) { bf16_t* rowp = base + (size_t)(row0 + ai * HALF + m * 16) * ld + col0;
; #pragma unroll
;                     for (int bj = 0; bj < 2; ++bj) { const f32x4 v0 = acc[ai][bj][m][0] * sc, v1 = acc[ai][bj][m][1] * sc;
;                         u32x4 w; w.x = cvt_pk_bf16(v0[0], v0[1]); w.y = cvt_pk_bf16(v0[2], v0[3]); w.z = cvt_pk_bf16(v1[0], v1[1]); w.w = cvt_pk_bf16(v1[2], v1[3]);
;                         __builtin_nontemporal_store(w, (u32x4*)(rowp + bj * HALF)); } }
.LBB0_215:
	s_cmp_lt_u32 s73, 14
	s_cselect_b64 s[60:61], -1, 0
	s_and_b64 s[66:67], s[60:61], exec
	s_cselect_b32 s13, -12, -14
	s_add_i32 s13, s13, s73
	s_and_b64 s[60:61], s[60:61], exec
	s_cselect_b32 s15, s1, s21
	s_cselect_b32 s33, s0, s20
	v_lshl_add_u32 v148, s58, 8, v150
	v_mov_b32_e32 v146, s33
	s_waitcnt lgkmcnt(0)
	v_mov_b32_e32 v147, s15
	v_lshl_or_b32 v162, s13, 8, v158
	v_mov_b32_e32 v163, v137
	v_ashrrev_i32_e32 v149, 31, v148
	s_cselect_b32 s13, 9, 11
	v_lshl_add_u64 v[146:147], v[162:163], 1, v[146:147]
	v_lshlrev_b64 v[162:163], s13, v[148:149]
	v_lshl_add_u64 v[166:167], v[162:163], 1, v[146:147]
	v_cvt_pk_bf16_f32 v162, v124, v125
	v_cvt_pk_bf16_f32 v163, v126, v127
	v_cvt_pk_bf16_f32 v164, v120, v121
	v_cvt_pk_bf16_f32 v165, v122, v123
	global_store_dwordx4 v[166:167], v[162:165], off sc0 sc1 nt
	s_nop 1
	v_cvt_pk_bf16_f32 v162, v68, v69
	v_cvt_pk_bf16_f32 v163, v70, v71
	v_cvt_pk_bf16_f32 v164, v64, v65
	v_cvt_pk_bf16_f32 v165, v66, v67
	global_store_dwordx4 v[166:167], v[162:165], off offset:256 sc0 sc1 nt
	s_nop 1
	v_or_b32_e32 v162, 16, v148
	v_ashrrev_i32_e32 v163, 31, v162
	v_lshlrev_b64 v[162:163], s13, v[162:163]
	v_lshl_add_u64 v[166:167], v[162:163], 1, v[146:147]
	v_cvt_pk_bf16_f32 v162, v116, v117
	v_cvt_pk_bf16_f32 v163, v118, v119
	v_cvt_pk_bf16_f32 v164, v112, v113
	v_cvt_pk_bf16_f32 v165, v114, v115
	global_store_dwordx4 v[166:167], v[162:165], off sc0 sc1 nt
	s_nop 1
	v_cvt_pk_bf16_f32 v162, v56, v57
	v_cvt_pk_bf16_f32 v163, v58, v59
	v_cvt_pk_bf16_f32 v164, v48, v49
	v_cvt_pk_bf16_f32 v165, v50, v51
	global_store_dwordx4 v[166:167], v[162:165], off offset:256 sc0 sc1 nt
	s_nop 1
	v_or_b32_e32 v162, 32, v148
	v_ashrrev_i32_e32 v163, 31, v162
	v_lshlrev_b64 v[162:163], s13, v[162:163]
	v_lshl_add_u64 v[166:167], v[162:163], 1, v[146:147]
	v_cvt_pk_bf16_f32 v162, v108, v109
	v_cvt_pk_bf16_f32 v163, v110, v111
	v_cvt_pk_bf16_f32 v164, v104, v105
	v_cvt_pk_bf16_f32 v165, v106, v107
	global_store_dwordx4 v[166:167], v[162:165], off sc0 sc1 nt
	s_nop 1
	v_cvt_pk_bf16_f32 v162, v44, v45
	v_cvt_pk_bf16_f32 v163, v46, v47
	v_cvt_pk_bf16_f32 v164, v40, v41
	v_cvt_pk_bf16_f32 v165, v42, v43
	global_store_dwordx4 v[166:167], v[162:165], off offset:256 sc0 sc1 nt
	s_nop 1
	v_or_b32_e32 v162, 48, v148
	v_ashrrev_i32_e32 v163, 31, v162
	v_lshlrev_b64 v[162:163], s13, v[162:163]
	v_lshl_add_u64 v[166:167], v[162:163], 1, v[146:147]
	v_cvt_pk_bf16_f32 v162, v100, v101
	v_cvt_pk_bf16_f32 v163, v102, v103
	v_cvt_pk_bf16_f32 v164, v96, v97
	v_cvt_pk_bf16_f32 v165, v98, v99
	global_store_dwordx4 v[166:167], v[162:165], off sc0 sc1 nt
	s_nop 1
	v_cvt_pk_bf16_f32 v162, v36, v37
	v_cvt_pk_bf16_f32 v163, v38, v39
	v_cvt_pk_bf16_f32 v164, v32, v33
	v_cvt_pk_bf16_f32 v165, v34, v35
	global_store_dwordx4 v[166:167], v[162:165], off offset:256 sc0 sc1 nt
	s_nop 1
	v_add_u32_e32 v162, 0x80, v148
	v_ashrrev_i32_e32 v163, 31, v162
	v_lshlrev_b64 v[162:163], s13, v[162:163]
	v_lshl_add_u64 v[166:167], v[162:163], 1, v[146:147]
	v_cvt_pk_bf16_f32 v162, v92, v93
	v_cvt_pk_bf16_f32 v163, v94, v95
	v_cvt_pk_bf16_f32 v164, v88, v89
	v_cvt_pk_bf16_f32 v165, v90, v91
	global_store_dwordx4 v[166:167], v[162:165], off sc0 sc1 nt
	s_nop 1
	v_cvt_pk_bf16_f32 v162, v28, v29
	v_cvt_pk_bf16_f32 v163, v30, v31
	v_cvt_pk_bf16_f32 v164, v24, v25
	v_cvt_pk_bf16_f32 v165, v26, v27
	global_store_dwordx4 v[166:167], v[162:165], off offset:256 sc0 sc1 nt
	s_nop 1
	v_add_u32_e32 v162, 0x90, v148
	v_ashrrev_i32_e32 v163, 31, v162
	v_lshlrev_b64 v[162:163], s13, v[162:163]
	v_lshl_add_u64 v[166:167], v[162:163], 1, v[146:147]
	v_cvt_pk_bf16_f32 v162, v84, v85
	v_cvt_pk_bf16_f32 v163, v86, v87
	v_cvt_pk_bf16_f32 v164, v80, v81
	v_cvt_pk_bf16_f32 v165, v82, v83
	global_store_dwordx4 v[166:167], v[162:165], off sc0 sc1 nt
	s_nop 1
	v_cvt_pk_bf16_f32 v162, v20, v21
	v_cvt_pk_bf16_f32 v163, v22, v23
	v_cvt_pk_bf16_f32 v164, v16, v17
	v_cvt_pk_bf16_f32 v165, v18, v19
	global_store_dwordx4 v[166:167], v[162:165], off offset:256 sc0 sc1 nt
	s_nop 1
	v_add_u32_e32 v162, 0xa0, v148
	v_ashrrev_i32_e32 v163, 31, v162
	v_lshlrev_b64 v[162:163], s13, v[162:163]
	v_add_u32_e32 v148, 0xb0, v148
	v_lshl_add_u64 v[166:167], v[162:163], 1, v[146:147]
	v_cvt_pk_bf16_f32 v162, v76, v77
	v_cvt_pk_bf16_f32 v163, v78, v79
	v_ashrrev_i32_e32 v149, 31, v148
	v_cvt_pk_bf16_f32 v164, v72, v73
	v_cvt_pk_bf16_f32 v165, v74, v75
	global_store_dwordx4 v[166:167], v[162:165], off sc0 sc1 nt
	v_lshlrev_b64 v[148:149], s13, v[148:149]
	s_nop 0
	v_cvt_pk_bf16_f32 v162, v12, v13
	v_cvt_pk_bf16_f32 v163, v14, v15
	v_cvt_pk_bf16_f32 v164, v8, v9
	v_cvt_pk_bf16_f32 v165, v10, v11
	global_store_dwordx4 v[166:167], v[162:165], off offset:256 sc0 sc1 nt
	s_nop 1
	v_lshl_add_u64 v[162:163], v[148:149], 1, v[146:147]
	v_cvt_pk_bf16_f32 v146, v60, v61
	v_cvt_pk_bf16_f32 v147, v62, v63
	v_cvt_pk_bf16_f32 v148, v52, v53
	v_cvt_pk_bf16_f32 v149, v54, v55
	global_store_dwordx4 v[162:163], v[146:149], off sc0 sc1 nt
	s_nop 1
	v_cvt_pk_bf16_f32 v146, v4, v5
	v_cvt_pk_bf16_f32 v147, v6, v7
	v_cvt_pk_bf16_f32 v148, v0, v1
	v_cvt_pk_bf16_f32 v149, v2, v3
	global_store_dwordx4 v[162:163], v[146:149], off offset:256 sc0 sc1 nt
	s_cbranch_execnz .LBB0_202

; __device__ __forceinline__ unsigned cvt_pk_bf16(float lo, float hi) { unsigned r; asm volatile("v_cvt_pk_bf16_f32 %0, %1, %2" : "=v"(r) : "v"(lo), "v"(hi)); return r; }
;     __device__ __forceinline__ void operator()(const f32x4 (&acc)[2][2][4][2], const Unit& u, int wr, int wc, int fr, int fq) const {
;     ...
;         if (HEADMAJOR && pn < 12) {
;             bf16_t* base; int ct; float sc = 1.f;
;             if (pn < 4) { base = Q; ct = pn; sc = qscale; } else if (pn < 8) { base = Kb; ct = pn - 4; } else { base = V; ct = pn - 8; }
;             const int b = u.pm >> 3, t0 = (u.pm & 7) * BM + wr * 64 + fr;
; #pragma unroll
;             for (int bj = 0; bj < 2; ++bj) { bf16_t* hb = base + ((size_t)((b * 8 + 2 * ct + bj) * 2048 + t0)) * 128 + wc * 32 + 8 * fq;
; #pragma unroll
;                 for (int ai = 0; ai < 2; ++ai)
; #pragma unroll
;                     for (int m = 0; m < 4; ++m) { const f32x4 v0 = acc[ai][bj][m][0] * sc, v1 = acc[ai][bj][m][1] * sc;
;                         u32x4 w; w.x = cvt_pk_bf16(v0[0], v0[1]); w.y = cvt_pk_bf16(v0[2], v0[3]); w.z = cvt_pk_bf16(v1[0], v1[1]); w.w = cvt_pk_bf16(v1[2], v1[3]);
;                         __builtin_nontemporal_store(w, (u32x4*)(hb + (ai * HALF + m * 16) * 128)); } }
.LBB0_223:
	s_lshl_b32 s13, s58, 8
	s_and_b32 s13, s13, 0x700
	s_add_u32 s66, s66, s22
	s_addc_u32 s67, s67, 0
	s_lshl_b32 s33, s58, 11
	s_lshl_b32 s15, s73, 12
	s_and_b32 s33, s33, 0xffffc000
	s_add_i32 s15, s15, s33
	s_or_b32 s13, s15, s13
	v_add_u32_e32 v148, s13, v150
	v_ashrrev_i32_e32 v149, 31, v148
	s_waitcnt lgkmcnt(0)
	v_lshl_add_u64 v[146:147], s[66:67], 0, v[136:137]
	v_lshlrev_b64 v[162:163], 8, v[148:149]
	v_lshl_add_u64 v[162:163], v[146:147], 0, v[162:163]
	v_pk_mul_f32 v[126:127], v[126:127], s[60:61] op_sel_hi:[1,0]
	v_pk_mul_f32 v[124:125], v[124:125], s[60:61] op_sel_hi:[1,0]
	v_pk_mul_f32 v[164:165], v[122:123], s[60:61] op_sel_hi:[1,0]
	v_pk_mul_f32 v[122:123], v[120:121], s[60:61] op_sel_hi:[1,0]
	v_cvt_pk_bf16_f32 v120, v124, v125
	v_cvt_pk_bf16_f32 v121, v126, v127
	v_pk_mul_f32 v[116:117], v[116:117], s[60:61] op_sel_hi:[1,0]
	v_cvt_pk_bf16_f32 v122, v122, v123
	v_cvt_pk_bf16_f32 v123, v164, v165
	global_store_dwordx4 v[162:163], v[120:123], off sc0 sc1 nt
	v_pk_mul_f32 v[118:119], v[118:119], s[60:61] op_sel_hi:[1,0]
	v_pk_mul_f32 v[110:111], v[110:111], s[60:61] op_sel_hi:[1,0]
	v_pk_mul_f32 v[120:121], v[114:115], s[60:61] op_sel_hi:[1,0]
	v_pk_mul_f32 v[114:115], v[112:113], s[60:61] op_sel_hi:[1,0]
	v_cvt_pk_bf16_f32 v112, v116, v117
	v_add_co_u32_e32 v116, vcc, s89, v162
	v_cvt_pk_bf16_f32 v113, v118, v119
	v_cvt_pk_bf16_f32 v114, v114, v115
	v_cvt_pk_bf16_f32 v115, v120, v121
	v_pk_mul_f32 v[108:109], v[108:109], s[60:61] op_sel_hi:[1,0]
	s_nop 0
	v_addc_co_u32_e32 v117, vcc, 0, v163, vcc
	global_store_dwordx4 v[116:117], v[112:115], off offset:-4096 sc0 sc1 nt
	v_pk_mul_f32 v[100:101], v[100:101], s[60:61] op_sel_hi:[1,0]
	v_pk_mul_f32 v[102:103], v[102:103], s[60:61] op_sel_hi:[1,0]
	v_pk_mul_f32 v[112:113], v[106:107], s[60:61] op_sel_hi:[1,0]
	v_pk_mul_f32 v[106:107], v[104:105], s[60:61] op_sel_hi:[1,0]
	v_cvt_pk_bf16_f32 v104, v108, v109
	v_cvt_pk_bf16_f32 v105, v110, v111
	v_pk_mul_f32 v[92:93], v[92:93], s[60:61] op_sel_hi:[1,0]
	v_cvt_pk_bf16_f32 v106, v106, v107
	v_cvt_pk_bf16_f32 v107, v112, v113
	global_store_dwordx4 v[116:117], v[104:107], off sc0 sc1 nt
	v_pk_mul_f32 v[94:95], v[94:95], s[60:61] op_sel_hi:[1,0]
	v_pk_mul_f32 v[86:87], v[86:87], s[60:61] op_sel_hi:[1,0]
	v_pk_mul_f32 v[104:105], v[98:99], s[60:61] op_sel_hi:[1,0]
	v_pk_mul_f32 v[98:99], v[96:97], s[60:61] op_sel_hi:[1,0]
	v_cvt_pk_bf16_f32 v96, v100, v101
	v_add_co_u32_e32 v100, vcc, s23, v162
	v_cvt_pk_bf16_f32 v97, v102, v103
	v_cvt_pk_bf16_f32 v98, v98, v99
	v_cvt_pk_bf16_f32 v99, v104, v105
	v_pk_mul_f32 v[84:85], v[84:85], s[60:61] op_sel_hi:[1,0]
	s_nop 0
	v_addc_co_u32_e32 v101, vcc, 0, v163, vcc
	global_store_dwordx4 v[100:101], v[96:99], off sc0 sc1 nt
	v_pk_mul_f32 v[76:77], v[76:77], s[60:61] op_sel_hi:[1,0]
	s_mov_b32 s13, 0xb000
	v_pk_mul_f32 v[96:97], v[90:91], s[60:61] op_sel_hi:[1,0]
	v_pk_mul_f32 v[90:91], v[88:89], s[60:61] op_sel_hi:[1,0]
	v_cvt_pk_bf16_f32 v88, v92, v93
	v_add_co_u32_e32 v92, vcc, s72, v162
	v_cvt_pk_bf16_f32 v89, v94, v95
	v_cvt_pk_bf16_f32 v90, v90, v91
	v_cvt_pk_bf16_f32 v91, v96, v97
	v_pk_mul_f32 v[78:79], v[78:79], s[60:61] op_sel_hi:[1,0]
	s_nop 0
	v_addc_co_u32_e32 v93, vcc, 0, v163, vcc
	global_store_dwordx4 v[92:93], v[88:91], off offset:-4096 sc0 sc1 nt
	v_pk_mul_f32 v[60:61], v[60:61], s[60:61] op_sel_hi:[1,0]
	v_pk_mul_f32 v[62:63], v[62:63], s[60:61] op_sel_hi:[1,0]
	v_pk_mul_f32 v[88:89], v[82:83], s[60:61] op_sel_hi:[1,0]
	v_pk_mul_f32 v[82:83], v[80:81], s[60:61] op_sel_hi:[1,0]
	v_cvt_pk_bf16_f32 v80, v84, v85
	v_cvt_pk_bf16_f32 v81, v86, v87
	v_pk_mul_f32 v[64:65], v[64:65], s[60:61] op_sel_hi:[1,0]
	v_cvt_pk_bf16_f32 v82, v82, v83
	v_cvt_pk_bf16_f32 v83, v88, v89
	global_store_dwordx4 v[92:93], v[80:83], off sc0 sc1 nt
	v_pk_mul_f32 v[46:47], v[46:47], s[60:61] op_sel_hi:[1,0]
	v_pk_mul_f32 v[44:45], v[44:45], s[60:61] op_sel_hi:[1,0]
	v_pk_mul_f32 v[80:81], v[74:75], s[60:61] op_sel_hi:[1,0]
	v_pk_mul_f32 v[74:75], v[72:73], s[60:61] op_sel_hi:[1,0]
	v_cvt_pk_bf16_f32 v72, v76, v77
	v_add_co_u32_e32 v76, vcc, s13, v162
	v_cvt_pk_bf16_f32 v73, v78, v79
	v_cvt_pk_bf16_f32 v74, v74, v75
	v_cvt_pk_bf16_f32 v75, v80, v81
	v_pk_mul_f32 v[36:37], v[36:37], s[60:61] op_sel_hi:[1,0]
	s_nop 0
	v_addc_co_u32_e32 v77, vcc, 0, v163, vcc
; __device__ __forceinline__ unsigned cvt_pk_bf16(float lo, float hi) { unsigned r; asm volatile("v_cvt_pk_bf16_f32 %0, %1, %2" : "=v"(r) : "v"(lo), "v"(hi)); return r; }
;     __device__ __forceinline__ void operator()(const f32x4 (&acc)[2][2][4][2], const Unit& u, int wr, int wc, int fr, int fq) const {
;     ...
;             for (int bj = 0; bj < 2; ++bj) { bf16_t* hb = base + ((size_t)((b * 8 + 2 * ct + bj) * 2048 + t0)) * 128 + wc * 32 + 8 * fq;
; #pragma unroll
;                 for (int ai = 0; ai < 2; ++ai)
; #pragma unroll
;                     for (int m = 0; m < 4; ++m) { const f32x4 v0 = acc[ai][bj][m][0] * sc, v1 = acc[ai][bj][m][1] * sc;
;                         u32x4 w; w.x = cvt_pk_bf16(v0[0], v0[1]); w.y = cvt_pk_bf16(v0[2], v0[3]); w.z = cvt_pk_bf16(v1[0], v1[1]); w.w = cvt_pk_bf16(v1[2], v1[3]);
;                         __builtin_nontemporal_store(w, (u32x4*)(hb + (ai * HALF + m * 16) * 128)); } }
	global_store_dwordx4 v[76:77], v[72:75], off offset:-4096 sc0 sc1 nt
	v_pk_mul_f32 v[38:39], v[38:39], s[60:61] op_sel_hi:[1,0]
	v_pk_mul_f32 v[28:29], v[28:29], s[60:61] op_sel_hi:[1,0]
	v_pk_mul_f32 v[72:73], v[54:55], s[60:61] op_sel_hi:[1,0]
	v_pk_mul_f32 v[54:55], v[52:53], s[60:61] op_sel_hi:[1,0]
	v_cvt_pk_bf16_f32 v52, v60, v61
	v_cvt_pk_bf16_f32 v53, v62, v63
	v_pk_mul_f32 v[62:63], v[66:67], s[60:61] op_sel_hi:[1,0]
	v_cvt_pk_bf16_f32 v54, v54, v55
	v_cvt_pk_bf16_f32 v55, v72, v73
	global_store_dwordx4 v[76:77], v[52:55], off sc0 sc1 nt
	v_pk_mul_f32 v[30:31], v[30:31], s[60:61] op_sel_hi:[1,0]
	v_pk_mul_f32 v[22:23], v[22:23], s[60:61] op_sel_hi:[1,0]
	v_add_u32_e32 v52, 0x800, v148
	v_ashrrev_i32_e32 v53, 31, v52
	v_lshlrev_b64 v[52:53], 8, v[52:53]
	v_lshl_add_u64 v[60:61], v[146:147], 0, v[52:53]
	v_pk_mul_f32 v[52:53], v[68:69], s[60:61] op_sel_hi:[1,0]
	v_pk_mul_f32 v[54:55], v[70:71], s[60:61] op_sel_hi:[1,0]
	v_cvt_pk_bf16_f32 v52, v52, v53
	v_pk_mul_f32 v[20:21], v[20:21], s[60:61] op_sel_hi:[1,0]
	v_cvt_pk_bf16_f32 v53, v54, v55
	v_cvt_pk_bf16_f32 v54, v64, v65
	v_cvt_pk_bf16_f32 v55, v62, v63
	global_store_dwordx4 v[60:61], v[52:55], off sc0 sc1 nt
	v_pk_mul_f32 v[12:13], v[12:13], s[60:61] op_sel_hi:[1,0]
	s_mov_b32 s13, 0xa000
	v_pk_mul_f32 v[52:53], v[58:59], s[60:61] op_sel_hi:[1,0]
	v_pk_mul_f32 v[54:55], v[56:57], s[60:61] op_sel_hi:[1,0]
	v_pk_mul_f32 v[56:57], v[50:51], s[60:61] op_sel_hi:[1,0]
	v_pk_mul_f32 v[50:51], v[48:49], s[60:61] op_sel_hi:[1,0]
	v_cvt_pk_bf16_f32 v48, v54, v55
	v_cvt_pk_bf16_f32 v49, v52, v53
	v_add_co_u32_e32 v52, vcc, s89, v60
	v_cvt_pk_bf16_f32 v50, v50, v51
	v_cvt_pk_bf16_f32 v51, v56, v57
	v_pk_mul_f32 v[14:15], v[14:15], s[60:61] op_sel_hi:[1,0]
	s_nop 0
	v_addc_co_u32_e32 v53, vcc, 0, v61, vcc
	global_store_dwordx4 v[52:53], v[48:51], off offset:-4096 sc0 sc1 nt
	v_pk_mul_f32 v[4:5], v[4:5], s[60:61] op_sel_hi:[1,0]
	v_pk_mul_f32 v[6:7], v[6:7], s[60:61] op_sel_hi:[1,0]
	v_pk_mul_f32 v[48:49], v[42:43], s[60:61] op_sel_hi:[1,0]
	v_pk_mul_f32 v[42:43], v[40:41], s[60:61] op_sel_hi:[1,0]
	v_cvt_pk_bf16_f32 v40, v44, v45
	v_cvt_pk_bf16_f32 v41, v46, v47
	s_nop 0
	v_cvt_pk_bf16_f32 v42, v42, v43
	v_cvt_pk_bf16_f32 v43, v48, v49
	global_store_dwordx4 v[52:53], v[40:43], off sc0 sc1 nt
	s_nop 1
	v_pk_mul_f32 v[40:41], v[34:35], s[60:61] op_sel_hi:[1,0]
	v_pk_mul_f32 v[34:35], v[32:33], s[60:61] op_sel_hi:[1,0]
	v_cvt_pk_bf16_f32 v32, v36, v37
	v_add_co_u32_e32 v36, vcc, s23, v60
	v_cvt_pk_bf16_f32 v33, v38, v39
	v_cvt_pk_bf16_f32 v34, v34, v35
	v_cvt_pk_bf16_f32 v35, v40, v41
	s_nop 1
	v_addc_co_u32_e32 v37, vcc, 0, v61, vcc
	global_store_dwordx4 v[36:37], v[32:35], off sc0 sc1 nt
	s_nop 1
	v_pk_mul_f32 v[32:33], v[26:27], s[60:61] op_sel_hi:[1,0]
	v_pk_mul_f32 v[26:27], v[24:25], s[60:61] op_sel_hi:[1,0]
	v_cvt_pk_bf16_f32 v24, v28, v29
	v_add_co_u32_e32 v28, vcc, s72, v60
	v_cvt_pk_bf16_f32 v25, v30, v31
	v_cvt_pk_bf16_f32 v26, v26, v27
	v_cvt_pk_bf16_f32 v27, v32, v33
	s_nop 1
	v_addc_co_u32_e32 v29, vcc, 0, v61, vcc
	global_store_dwordx4 v[28:29], v[24:27], off offset:-4096 sc0 sc1 nt
	s_nop 1
	v_pk_mul_f32 v[24:25], v[18:19], s[60:61] op_sel_hi:[1,0]
	v_pk_mul_f32 v[18:19], v[16:17], s[60:61] op_sel_hi:[1,0]
	v_cvt_pk_bf16_f32 v16, v20, v21
	v_cvt_pk_bf16_f32 v17, v22, v23
	s_nop 0
	v_cvt_pk_bf16_f32 v18, v18, v19
	v_cvt_pk_bf16_f32 v19, v24, v25
	global_store_dwordx4 v[28:29], v[16:19], off sc0 sc1 nt
	s_nop 1
	v_pk_mul_f32 v[16:17], v[10:11], s[60:61] op_sel_hi:[1,0]
	v_pk_mul_f32 v[10:11], v[8:9], s[60:61] op_sel_hi:[1,0]
	v_cvt_pk_bf16_f32 v8, v12, v13
	v_add_co_u32_e32 v12, vcc, s13, v60
	v_cvt_pk_bf16_f32 v9, v14, v15
	v_cvt_pk_bf16_f32 v10, v10, v11
	v_cvt_pk_bf16_f32 v11, v16, v17
	s_nop 1
	v_addc_co_u32_e32 v13, vcc, 0, v61, vcc
	global_store_dwordx4 v[12:13], v[8:11], off sc0 sc1 nt
	s_nop 1
	v_pk_mul_f32 v[8:9], v[2:3], s[60:61] op_sel_hi:[1,0]
	v_pk_mul_f32 v[2:3], v[0:1], s[60:61] op_sel_hi:[1,0]
	v_cvt_pk_bf16_f32 v0, v4, v5
	v_add_co_u32_e32 v4, vcc, 0xb000, v60
	v_cvt_pk_bf16_f32 v1, v6, v7
	v_cvt_pk_bf16_f32 v2, v2, v3
	v_cvt_pk_bf16_f32 v3, v8, v9
	s_nop 1
	v_addc_co_u32_e32 v5, vcc, 0, v61, vcc
	global_store_dwordx4 v[4:5], v[0:3], off sc0 sc1 nt
	s_andn2_b64 vcc, exec, s[4:5]
	s_mov_b64 s[4:5], -1
	s_cbranch_vccnz .LBB0_193
